# previous + GEMM3>GEMM4 barrier XCD-local too, with write-after-read waits on the neighbouring groups' counters (10 of 14 barriers local)
# speedup vs baseline: 1.0435x; 1.0133x over previous
; __global__ void __launch_bounds__(NWAVES * 64, 2) fwd_kernel(Args args) {
;     ...
;         if (ph + 1 < args.ph_hi || rep + 1 < nrep) { if (args.ph_hi > 1000) grid.sync(); else xcd_barrier(xb); } else __syncthreads();
cvx_decided:
	s_mov_b32 s2, 0x7af4
	s_bitcmp1_b32 s2, s10
	s_cbranch_scc0 cvx_fullbar
	s_cmp_eq_u32 s101, 1
	s_cbranch_scc0 cvx_fullbar
	v_readlane_b32 s22, v253, 12
	v_readlane_b32 s23, v253, 13
	v_mov_b32_e32 v3, 0
	v_mov_b32_e32 v0, 1
	s_and_b32 s2, s89, 7
	s_lshl_b32 s2, s2, 7
	s_add_i32 s2, s2, 0x3600
	s_add_u32 s22, s22, s2
	s_addc_u32 s23, s23, 0
	global_atomic_add v1, v3, v0, s[22:23] sc0
	s_waitcnt vmcnt(0)
	v_readfirstlane_b32 s2, v1
	s_nop 0
	s_lshr_b32 s3, s2, 5
	s_add_i32 s3, s3, 1
	s_lshl_b32 s3, s3, 5
	s_mov_b32 s2, 0

; __global__ void __launch_bounds__(NWAVES * 64, 2) fwd_kernel(Args args) {
;     ...
;         if (ph + 1 < args.ph_hi || rep + 1 < nrep) { if (args.ph_hi > 1000) grid.sync(); else xcd_barrier(xb); } else __syncthreads();
cvx_arrived:
	s_and_b32 s2, s89, 7
	s_mov_b32 s35, 1
	s_cmp_eq_u32 s10, 5
	s_cbranch_scc1 cvx_w45a
	s_cmp_eq_u32 s10, 12
	s_cbranch_scc1 cvx_w45b
	s_cmp_eq_u32 s10, 14
	s_cbranch_scc1 cvx_w67
	s_branch cvx_done
cvx_w45a:
	s_movk_i32 s3, 64
	s_branch cvx_w45
cvx_w45b:
	s_movk_i32 s3, 224
cvx_w45:
	s_cmp_eq_u32 s2, 0
	s_cbranch_scc1 cvx_done
	s_sub_u32 s22, s22, 0x80
	s_subb_u32 s23, s23, 0
	s_branch cvx_waitn
cvx_w67:
	s_cmp_gt_u32 s2, 3
	s_cbranch_scc1 cvx_done
	s_movk_i32 s3, 256
	s_mov_b32 s35, 2
	s_lshl_b32 s2, s2, 7
	s_add_u32 s22, s22, s2
	s_addc_u32 s23, s23, 0
cvx_waitn:
	s_mov_b32 s2, 0
cvx_wspin:
	global_load_dword v0, v3, s[22:23] sc1
	s_waitcnt vmcnt(0)
	v_readfirstlane_b32 s34, v0
	s_nop 0
	s_cmp_ge_u32 s34, s3
	s_cbranch_scc1 cvx_wok
	s_sleep 1
	s_add_i32 s2, s2, 1
	s_cmp_lt_u32 s2, 0x100000
	s_cbranch_scc1 cvx_wspin
cvx_wok:
	s_sub_u32 s35, s35, 1
	s_cmp_eq_u32 s35, 0
	s_cbranch_scc1 cvx_done
	s_add_u32 s22, s22, 0x80
	s_addc_u32 s23, s23, 0
	s_branch cvx_waitn
cvx_done:
	buffer_inv sc0
	s_branch .LBB0_486
